# v11 + K-loop: s_setprio 1 in front of the loader's waits, s_setprio 0 behind the first LDS read of each load segment
# speedup vs baseline: 1.0080x; 1.0080x over previous
.LBB0_344:
	s_add_i32 s4, s2, 2
	s_add_u32 s5, s68, s0
	s_addc_u32 s3, s69, s1
	s_add_u32 s33, s86, s0
	s_addc_u32 s35, s87, s1
	s_add_i32 s47, 0, 0x10000
	s_cmp_eq_u32 s21, s2
	s_cselect_b32 s3, s65, s3
	s_cselect_b32 s2, s64, s5
	v_add_u32_e32 v17, s47, v237
	s_cselect_b32 s57, s67, s35
	s_cselect_b32 s56, s66, s33
	s_add_i32 s5, 0, 0x14000
	ds_read_b128 v[134:137], v17
	s_setprio 0
	ds_read_b128 v[138:141], v17 offset:1024
	ds_read_b128 v[142:145], v17 offset:2048
	ds_read_b128 v[146:149], v17 offset:3072
	v_add_u32_e32 v17, s5, v237
	ds_read_b128 v[150:153], v17
	ds_read_b128 v[154:157], v17 offset:1024
	ds_read_b128 v[158:161], v17 offset:2048
	ds_read_b128 v[162:165], v17 offset:3072
	v_lshl_add_u64 v[170:171], s[68:69], 0, v[132:133]
	s_add_i32 m0, s37, 0xc000
	ds_read_b128 v[166:169], v240
	ds_read_b128 v[186:189], v240 offset:1024
	ds_read_b128 v[190:193], v240 offset:2048
	ds_read_b128 v[194:197], v240 offset:3072
	ds_read_b128 v[198:201], v240 offset:4096
	ds_read_b128 v[202:205], v240 offset:5120
	ds_read_b128 v[206:209], v240 offset:6144
	ds_read_b128 v[210:213], v240 offset:7168
	global_load_lds_dwordx4 v[170:171], off
	v_lshl_add_u64 v[170:171], s[68:69], 0, v[18:19]
	s_add_i32 m0, s37, 0xe000
	s_nop 0
	global_load_lds_dwordx4 v[170:171], off
	s_setprio 1
	s_waitcnt vmcnt(8)
	s_waitcnt lgkmcnt(0)
	s_barrier
	v_mfma_f32_16x16x32_bf16 v[8:11], v[134:137], v[166:169], v[8:11]
	v_mfma_f32_16x16x32_bf16 v[12:15], v[142:145], v[166:169], v[12:15]
	v_mfma_f32_16x16x32_bf16 v[28:31], v[134:137], v[190:193], v[28:31]
	v_mfma_f32_16x16x32_bf16 v[32:35], v[142:145], v[190:193], v[32:35]
	v_mfma_f32_16x16x32_bf16 v[36:39], v[134:137], v[198:201], v[36:39]
	v_mfma_f32_16x16x32_bf16 v[44:47], v[142:145], v[198:201], v[44:47]
	v_mfma_f32_16x16x32_bf16 v[80:83], v[134:137], v[206:209], v[80:83]
	v_mfma_f32_16x16x32_bf16 v[88:91], v[142:145], v[206:209], v[88:91]
	v_mfma_f32_16x16x32_bf16 v[8:11], v[138:141], v[186:189], v[8:11]
	v_mfma_f32_16x16x32_bf16 v[12:15], v[146:149], v[186:189], v[12:15]
	v_mfma_f32_16x16x32_bf16 v[28:31], v[138:141], v[194:197], v[28:31]
	v_mfma_f32_16x16x32_bf16 v[32:35], v[146:149], v[194:197], v[32:35]
	v_mfma_f32_16x16x32_bf16 v[36:39], v[138:141], v[202:205], v[36:39]
	v_mfma_f32_16x16x32_bf16 v[44:47], v[146:149], v[202:205], v[44:47]
	v_mfma_f32_16x16x32_bf16 v[80:83], v[138:141], v[210:213], v[80:83]
	v_mfma_f32_16x16x32_bf16 v[88:91], v[146:149], v[210:213], v[88:91]
	v_mfma_f32_16x16x32_bf16 v[0:3], v[150:153], v[166:169], v[0:3]
	v_mfma_f32_16x16x32_bf16 v[4:7], v[158:161], v[166:169], v[4:7]
	v_mfma_f32_16x16x32_bf16 v[20:23], v[150:153], v[190:193], v[20:23]
	v_mfma_f32_16x16x32_bf16 v[24:27], v[158:161], v[190:193], v[24:27]
	v_mfma_f32_16x16x32_bf16 v[40:43], v[150:153], v[198:201], v[40:43]
	v_mfma_f32_16x16x32_bf16 v[48:51], v[158:161], v[198:201], v[48:51]
	v_mfma_f32_16x16x32_bf16 v[60:63], v[150:153], v[206:209], v[60:63]
	v_mfma_f32_16x16x32_bf16 v[64:67], v[158:161], v[206:209], v[64:67]
	v_mfma_f32_16x16x32_bf16 v[0:3], v[154:157], v[186:189], v[0:3]
	v_mfma_f32_16x16x32_bf16 v[4:7], v[162:165], v[186:189], v[4:7]
	v_mfma_f32_16x16x32_bf16 v[20:23], v[154:157], v[194:197], v[20:23]
	v_mfma_f32_16x16x32_bf16 v[24:27], v[162:165], v[194:197], v[24:27]
	v_mfma_f32_16x16x32_bf16 v[40:43], v[154:157], v[202:205], v[40:43]
	v_mfma_f32_16x16x32_bf16 v[48:51], v[162:165], v[202:205], v[48:51]
	v_mfma_f32_16x16x32_bf16 v[60:63], v[154:157], v[210:213], v[60:63]
	v_mfma_f32_16x16x32_bf16 v[64:67], v[162:165], v[210:213], v[64:67]
	s_barrier
	s_add_i32 s33, s47, s17
	v_lshl_add_u64 v[170:171], s[56:57], 0, v[174:175]
	s_mov_b32 m0, s33
	ds_read_b128 v[166:169], v240 offset:16384
	s_setprio 0
	ds_read_b128 v[186:189], v240 offset:17408
	ds_read_b128 v[190:193], v240 offset:18432
	ds_read_b128 v[194:197], v240 offset:19456
	ds_read_b128 v[198:201], v240 offset:20480
	ds_read_b128 v[202:205], v240 offset:21504
	ds_read_b128 v[206:209], v240 offset:22528
	ds_read_b128 v[210:213], v240 offset:23552
	global_load_lds_dwordx4 v[170:171], off
	s_add_i32 m0, s33, 0x2000
	v_lshl_add_u64 v[214:215], s[56:57], 0, v[178:179]
	s_add_u32 s56, s56, s36
	s_addc_u32 s57, s57, 0
	s_add_i32 s5, s5, s17
	global_load_lds_dwordx4 v[214:215], off
	v_lshl_add_u64 v[216:217], s[56:57], 0, v[174:175]
	s_mov_b32 m0, s5
	v_lshl_add_u64 v[224:225], s[56:57], 0, v[178:179]
	global_load_lds_dwordx4 v[216:217], off
	s_add_i32 m0, s5, 0x2000
	v_lshl_add_u64 v[226:227], s[2:3], 0, v[172:173]
	global_load_lds_dwordx4 v[224:225], off
	s_mov_b32 m0, s37
	v_lshl_add_u64 v[242:243], s[2:3], 0, v[176:177]
	global_load_lds_dwordx4 v[226:227], off
	s_mov_b32 m0, s45
	s_nop 0
	global_load_lds_dwordx4 v[242:243], off
	s_setprio 1
	s_waitcnt vmcnt(8)
	s_waitcnt lgkmcnt(0)
	s_barrier
	v_mfma_f32_16x16x32_bf16 v[68:71], v[134:137], v[166:169], v[68:71]
	v_mfma_f32_16x16x32_bf16 v[72:75], v[142:145], v[166:169], v[72:75]
	v_mfma_f32_16x16x32_bf16 v[92:95], v[134:137], v[190:193], v[92:95]
	v_mfma_f32_16x16x32_bf16 v[96:99], v[142:145], v[190:193], v[96:99]
	v_mfma_f32_16x16x32_bf16 v[108:111], v[134:137], v[198:201], v[108:111]
	v_mfma_f32_16x16x32_bf16 v[112:115], v[142:145], v[198:201], v[112:115]
	v_mfma_f32_16x16x32_bf16 v[124:127], v[134:137], v[206:209], v[124:127]
	v_mfma_f32_16x16x32_bf16 v[128:131], v[142:145], v[206:209], v[128:131]
	v_mfma_f32_16x16x32_bf16 v[68:71], v[138:141], v[186:189], v[68:71]
	v_mfma_f32_16x16x32_bf16 v[72:75], v[146:149], v[186:189], v[72:75]
	v_mfma_f32_16x16x32_bf16 v[92:95], v[138:141], v[194:197], v[92:95]
	v_mfma_f32_16x16x32_bf16 v[96:99], v[146:149], v[194:197], v[96:99]
	v_mfma_f32_16x16x32_bf16 v[108:111], v[138:141], v[202:205], v[108:111]
	v_mfma_f32_16x16x32_bf16 v[112:115], v[146:149], v[202:205], v[112:115]
	v_mfma_f32_16x16x32_bf16 v[124:127], v[138:141], v[210:213], v[124:127]
	v_mfma_f32_16x16x32_bf16 v[128:131], v[146:149], v[210:213], v[128:131]
	v_mfma_f32_16x16x32_bf16 v[52:55], v[150:153], v[166:169], v[52:55]
	v_mfma_f32_16x16x32_bf16 v[56:59], v[158:161], v[166:169], v[56:59]
	v_mfma_f32_16x16x32_bf16 v[76:79], v[150:153], v[190:193], v[76:79]
	v_mfma_f32_16x16x32_bf16 v[84:87], v[158:161], v[190:193], v[84:87]
	v_mfma_f32_16x16x32_bf16 v[100:103], v[150:153], v[198:201], v[100:103]
	v_mfma_f32_16x16x32_bf16 v[104:107], v[158:161], v[198:201], v[104:107]
	v_mfma_f32_16x16x32_bf16 v[116:119], v[150:153], v[206:209], v[116:119]
	v_mfma_f32_16x16x32_bf16 v[120:123], v[158:161], v[206:209], v[120:123]
	v_mfma_f32_16x16x32_bf16 v[52:55], v[154:157], v[186:189], v[52:55]
	v_mfma_f32_16x16x32_bf16 v[56:59], v[162:165], v[186:189], v[56:59]
	v_mfma_f32_16x16x32_bf16 v[76:79], v[154:157], v[194:197], v[76:79]
	v_mfma_f32_16x16x32_bf16 v[84:87], v[162:165], v[194:197], v[84:87]
	v_mfma_f32_16x16x32_bf16 v[100:103], v[154:157], v[202:205], v[100:103]
	v_mfma_f32_16x16x32_bf16 v[104:107], v[162:165], v[202:205], v[104:107]
	v_mfma_f32_16x16x32_bf16 v[116:119], v[154:157], v[210:213], v[116:119]
	v_mfma_f32_16x16x32_bf16 v[120:123], v[162:165], v[210:213], v[120:123]
	s_barrier
	s_add_i32 s5, 0, 0x18000
	v_add_u32_e32 v17, s5, v237
	s_add_i32 s33, 0, 0x1c000
	ds_read_b128 v[134:137], v17
	s_setprio 0
	ds_read_b128 v[138:141], v17 offset:1024
	ds_read_b128 v[142:145], v17 offset:2048
	ds_read_b128 v[146:149], v17 offset:3072
	v_add_u32_e32 v17, s33, v237
	ds_read_b128 v[150:153], v17
	ds_read_b128 v[154:157], v17 offset:1024
	ds_read_b128 v[158:161], v17 offset:2048
	ds_read_b128 v[162:165], v17 offset:3072
	s_add_u32 s2, s2, s36
	s_addc_u32 s3, s3, 0
	s_mov_b32 m0, s26
	v_lshl_add_u64 v[244:245], s[2:3], 0, v[172:173]
	ds_read_b128 v[166:169], v240 offset:32768
	ds_read_b128 v[186:189], v240 offset:33792
	ds_read_b128 v[190:193], v240 offset:34816
	ds_read_b128 v[194:197], v240 offset:35840
	ds_read_b128 v[198:201], v240 offset:36864
	ds_read_b128 v[202:205], v240 offset:37888
	ds_read_b128 v[206:209], v240 offset:38912
	ds_read_b128 v[210:213], v240 offset:39936
	global_load_lds_dwordx4 v[244:245], off
	v_lshl_add_u64 v[244:245], s[2:3], 0, v[176:177]
	s_mov_b32 m0, s27
	s_nop 0
	global_load_lds_dwordx4 v[244:245], off
	s_setprio 1
	s_waitcnt vmcnt(8)
	s_waitcnt lgkmcnt(0)
	s_barrier
	v_mfma_f32_16x16x32_bf16 v[8:11], v[134:137], v[166:169], v[8:11]
	v_mfma_f32_16x16x32_bf16 v[12:15], v[142:145], v[166:169], v[12:15]
	v_mfma_f32_16x16x32_bf16 v[28:31], v[134:137], v[190:193], v[28:31]
	v_mfma_f32_16x16x32_bf16 v[32:35], v[142:145], v[190:193], v[32:35]
	v_mfma_f32_16x16x32_bf16 v[36:39], v[134:137], v[198:201], v[36:39]
	v_mfma_f32_16x16x32_bf16 v[44:47], v[142:145], v[198:201], v[44:47]
	v_mfma_f32_16x16x32_bf16 v[80:83], v[134:137], v[206:209], v[80:83]
	v_mfma_f32_16x16x32_bf16 v[88:91], v[142:145], v[206:209], v[88:91]
	v_mfma_f32_16x16x32_bf16 v[8:11], v[138:141], v[186:189], v[8:11]
	v_mfma_f32_16x16x32_bf16 v[12:15], v[146:149], v[186:189], v[12:15]
	v_mfma_f32_16x16x32_bf16 v[28:31], v[138:141], v[194:197], v[28:31]
	v_mfma_f32_16x16x32_bf16 v[32:35], v[146:149], v[194:197], v[32:35]
	v_mfma_f32_16x16x32_bf16 v[36:39], v[138:141], v[202:205], v[36:39]
	v_mfma_f32_16x16x32_bf16 v[44:47], v[146:149], v[202:205], v[44:47]
	v_mfma_f32_16x16x32_bf16 v[80:83], v[138:141], v[210:213], v[80:83]
	v_mfma_f32_16x16x32_bf16 v[88:91], v[146:149], v[210:213], v[88:91]
	v_mfma_f32_16x16x32_bf16 v[0:3], v[150:153], v[166:169], v[0:3]
	v_mfma_f32_16x16x32_bf16 v[4:7], v[158:161], v[166:169], v[4:7]
	v_mfma_f32_16x16x32_bf16 v[20:23], v[150:153], v[190:193], v[20:23]
	v_mfma_f32_16x16x32_bf16 v[24:27], v[158:161], v[190:193], v[24:27]
	v_mfma_f32_16x16x32_bf16 v[40:43], v[150:153], v[198:201], v[40:43]
	v_mfma_f32_16x16x32_bf16 v[48:51], v[158:161], v[198:201], v[48:51]
	v_mfma_f32_16x16x32_bf16 v[60:63], v[150:153], v[206:209], v[60:63]
	v_mfma_f32_16x16x32_bf16 v[64:67], v[158:161], v[206:209], v[64:67]
	v_mfma_f32_16x16x32_bf16 v[0:3], v[154:157], v[186:189], v[0:3]
	v_mfma_f32_16x16x32_bf16 v[4:7], v[162:165], v[186:189], v[4:7]
	v_mfma_f32_16x16x32_bf16 v[20:23], v[154:157], v[194:197], v[20:23]
	v_mfma_f32_16x16x32_bf16 v[24:27], v[162:165], v[194:197], v[24:27]
	v_mfma_f32_16x16x32_bf16 v[40:43], v[154:157], v[202:205], v[40:43]
	v_mfma_f32_16x16x32_bf16 v[48:51], v[162:165], v[202:205], v[48:51]
	v_mfma_f32_16x16x32_bf16 v[60:63], v[154:157], v[210:213], v[60:63]
	v_mfma_f32_16x16x32_bf16 v[64:67], v[162:165], v[210:213], v[64:67]
	s_barrier
	s_add_i32 s2, s5, s17
	v_lshl_add_u64 v[170:171], v[170:171], 0, s[6:7]
	s_mov_b32 m0, s2
	ds_read_b128 v[166:169], v240 offset:49152
	s_setprio 0
	ds_read_b128 v[186:189], v240 offset:50176
	ds_read_b128 v[190:193], v240 offset:51200
	ds_read_b128 v[194:197], v240 offset:52224
	ds_read_b128 v[198:201], v240 offset:53248
	ds_read_b128 v[202:205], v240 offset:54272
	ds_read_b128 v[206:209], v240 offset:55296
	ds_read_b128 v[210:213], v240 offset:56320
	global_load_lds_dwordx4 v[170:171], off
	v_lshl_add_u64 v[170:171], v[214:215], 0, s[6:7]
	s_add_i32 m0, s2, 0x2000
	s_add_i32 s2, s33, s17
	global_load_lds_dwordx4 v[170:171], off
	v_lshl_add_u64 v[170:171], v[216:217], 0, s[6:7]
	s_mov_b32 m0, s2
	s_nop 0
	global_load_lds_dwordx4 v[170:171], off
	v_lshl_add_u64 v[170:171], v[224:225], 0, s[6:7]
	s_add_i32 m0, s2, 0x2000
	s_nop 0
	global_load_lds_dwordx4 v[170:171], off
	v_lshl_add_u64 v[170:171], v[226:227], 0, s[6:7]
	s_mov_b32 m0, s63
	s_nop 0
	global_load_lds_dwordx4 v[170:171], off
	v_lshl_add_u64 v[170:171], v[242:243], 0, s[6:7]
	s_mov_b32 m0, s20
	s_nop 0
	global_load_lds_dwordx4 v[170:171], off
	s_setprio 1
	s_waitcnt vmcnt(8)
	s_waitcnt lgkmcnt(0)
	s_barrier
	v_mfma_f32_16x16x32_bf16 v[68:71], v[134:137], v[166:169], v[68:71]
	v_mfma_f32_16x16x32_bf16 v[72:75], v[142:145], v[166:169], v[72:75]
	v_mfma_f32_16x16x32_bf16 v[92:95], v[134:137], v[190:193], v[92:95]
	v_mfma_f32_16x16x32_bf16 v[96:99], v[142:145], v[190:193], v[96:99]
	v_mfma_f32_16x16x32_bf16 v[108:111], v[134:137], v[198:201], v[108:111]
	v_mfma_f32_16x16x32_bf16 v[112:115], v[142:145], v[198:201], v[112:115]
	v_mfma_f32_16x16x32_bf16 v[124:127], v[134:137], v[206:209], v[124:127]
	v_mfma_f32_16x16x32_bf16 v[128:131], v[142:145], v[206:209], v[128:131]
	v_mfma_f32_16x16x32_bf16 v[68:71], v[138:141], v[186:189], v[68:71]
	v_mfma_f32_16x16x32_bf16 v[72:75], v[146:149], v[186:189], v[72:75]
	v_mfma_f32_16x16x32_bf16 v[92:95], v[138:141], v[194:197], v[92:95]
	v_mfma_f32_16x16x32_bf16 v[96:99], v[146:149], v[194:197], v[96:99]
	v_mfma_f32_16x16x32_bf16 v[108:111], v[138:141], v[202:205], v[108:111]
	v_mfma_f32_16x16x32_bf16 v[112:115], v[146:149], v[202:205], v[112:115]
	v_mfma_f32_16x16x32_bf16 v[124:127], v[138:141], v[210:213], v[124:127]
	v_mfma_f32_16x16x32_bf16 v[128:131], v[146:149], v[210:213], v[128:131]
	v_mfma_f32_16x16x32_bf16 v[52:55], v[150:153], v[166:169], v[52:55]
	v_mfma_f32_16x16x32_bf16 v[56:59], v[158:161], v[166:169], v[56:59]
	v_mfma_f32_16x16x32_bf16 v[76:79], v[150:153], v[190:193], v[76:79]
	v_mfma_f32_16x16x32_bf16 v[84:87], v[158:161], v[190:193], v[84:87]
	v_mfma_f32_16x16x32_bf16 v[100:103], v[150:153], v[198:201], v[100:103]
	v_mfma_f32_16x16x32_bf16 v[104:107], v[158:161], v[198:201], v[104:107]
	v_mfma_f32_16x16x32_bf16 v[116:119], v[150:153], v[206:209], v[116:119]
	v_mfma_f32_16x16x32_bf16 v[120:123], v[158:161], v[206:209], v[120:123]
	v_mfma_f32_16x16x32_bf16 v[52:55], v[154:157], v[186:189], v[52:55]
	v_mfma_f32_16x16x32_bf16 v[56:59], v[162:165], v[186:189], v[56:59]
	v_mfma_f32_16x16x32_bf16 v[76:79], v[154:157], v[194:197], v[76:79]
	v_mfma_f32_16x16x32_bf16 v[84:87], v[162:165], v[194:197], v[84:87]
	v_mfma_f32_16x16x32_bf16 v[100:103], v[154:157], v[202:205], v[100:103]
	v_mfma_f32_16x16x32_bf16 v[104:107], v[162:165], v[202:205], v[104:107]
	v_mfma_f32_16x16x32_bf16 v[116:119], v[154:157], v[210:213], v[116:119]
	v_mfma_f32_16x16x32_bf16 v[120:123], v[162:165], v[210:213], v[120:123]
	s_barrier
	s_add_u32 s0, s0, 0x100
	s_addc_u32 s1, s1, 0
	v_lshl_add_u64 v[132:133], v[132:133], 0, s[8:9]
	v_lshl_add_u64 v[18:19], v[18:19], 0, s[8:9]
	s_cmp_ge_u32 s4, s62
	s_mov_b32 s2, s4
	s_cbranch_scc0 .LBB0_344
	s_setprio 0
	v_readlane_b32 s0, v253, 40
	v_readlane_b32 s1, v253, 41
	s_and_b64 vcc, exec, s[0:1]
	s_cbranch_vccz .LBB0_347
	s_barrier
